# v29 + M0 formed directly + loop-end updates inside the last compute segment (v30 and v31 combined)
# baseline (speedup 1.0000x reference)
.LBB0_134:
	s_add_u32 s0, s34, 0xfff00080
	s_addc_u32 s1, s35, -1
	s_cmp_eq_u32 s60, 60
	s_cselect_b32 s39, s12, s1
	s_cselect_b32 s38, s13, s0
	s_cselect_b32 s37, s15, s59
	s_cselect_b32 s36, s57, s58
	s_add_i32 m0, s29, 0xc000
	ds_read_b128 v[148:151], v156
	global_load_lds_dwordx4 v140, s[34:35]
	s_add_i32 m0, s29, 0xe000
	ds_read_b128 v[160:163], v156 offset:1024
	global_load_lds_dwordx4 v142, s[34:35]
	ds_read_b128 v[164:167], v156 offset:2048
	ds_read_b128 v[168:171], v156 offset:3072
	ds_read_b128 v[172:175], v157
	ds_read_b128 v[176:179], v157 offset:1024
	ds_read_b128 v[180:183], v157 offset:2048
	ds_read_b128 v[184:187], v157 offset:3072
	ds_read_b128 v[188:191], v158
	ds_read_b128 v[192:195], v158 offset:1024
	ds_read_b128 v[196:199], v158 offset:2048
	ds_read_b128 v[200:203], v158 offset:3072
	ds_read_b128 v[208:211], v158 offset:4096
	ds_read_b128 v[212:215], v158 offset:5120
	ds_read_b128 v[216:219], v158 offset:6144
	ds_read_b128 v[220:223], v158 offset:7168
	s_waitcnt vmcnt(8) lgkmcnt(0)
	s_setprio 3
	s_barrier
	v_mfma_f32_16x16x32_bf16 v[124:127], v[148:151], v[188:191], v[124:127]
	v_mfma_f32_16x16x32_bf16 v[120:123], v[164:167], v[188:191], v[120:123]
	v_mfma_f32_16x16x32_bf16 v[108:111], v[148:151], v[196:199], v[108:111]
	v_mfma_f32_16x16x32_bf16 v[104:107], v[164:167], v[196:199], v[104:107]
	v_mfma_f32_16x16x32_bf16 v[92:95], v[148:151], v[208:211], v[92:95]
	v_mfma_f32_16x16x32_bf16 v[88:91], v[164:167], v[208:211], v[88:91]
	v_mfma_f32_16x16x32_bf16 v[76:79], v[148:151], v[216:219], v[76:79]
	v_mfma_f32_16x16x32_bf16 v[72:75], v[164:167], v[216:219], v[72:75]
	v_mfma_f32_16x16x32_bf16 v[124:127], v[160:163], v[192:195], v[124:127]
	v_mfma_f32_16x16x32_bf16 v[120:123], v[168:171], v[192:195], v[120:123]
	v_mfma_f32_16x16x32_bf16 v[108:111], v[160:163], v[200:203], v[108:111]
	v_mfma_f32_16x16x32_bf16 v[104:107], v[168:171], v[200:203], v[104:107]
	v_mfma_f32_16x16x32_bf16 v[92:95], v[160:163], v[212:215], v[92:95]
	v_mfma_f32_16x16x32_bf16 v[88:91], v[168:171], v[212:215], v[88:91]
	v_mfma_f32_16x16x32_bf16 v[76:79], v[160:163], v[220:223], v[76:79]
	v_mfma_f32_16x16x32_bf16 v[72:75], v[168:171], v[220:223], v[72:75]
	v_mfma_f32_16x16x32_bf16 v[116:119], v[172:175], v[188:191], v[116:119]
	v_mfma_f32_16x16x32_bf16 v[112:115], v[180:183], v[188:191], v[112:115]
	v_mfma_f32_16x16x32_bf16 v[100:103], v[172:175], v[196:199], v[100:103]
	v_mfma_f32_16x16x32_bf16 v[96:99], v[180:183], v[196:199], v[96:99]
	v_mfma_f32_16x16x32_bf16 v[84:87], v[172:175], v[208:211], v[84:87]
	v_mfma_f32_16x16x32_bf16 v[80:83], v[180:183], v[208:211], v[80:83]
	v_mfma_f32_16x16x32_bf16 v[68:71], v[172:175], v[216:219], v[68:71]
	v_mfma_f32_16x16x32_bf16 v[64:67], v[180:183], v[216:219], v[64:67]
	v_mfma_f32_16x16x32_bf16 v[116:119], v[176:179], v[192:195], v[116:119]
	v_mfma_f32_16x16x32_bf16 v[112:115], v[184:187], v[192:195], v[112:115]
	v_mfma_f32_16x16x32_bf16 v[100:103], v[176:179], v[200:203], v[100:103]
	v_mfma_f32_16x16x32_bf16 v[96:99], v[184:187], v[200:203], v[96:99]
	v_mfma_f32_16x16x32_bf16 v[84:87], v[176:179], v[212:215], v[84:87]
	v_mfma_f32_16x16x32_bf16 v[80:83], v[184:187], v[212:215], v[80:83]
	v_mfma_f32_16x16x32_bf16 v[68:71], v[176:179], v[220:223], v[68:71]
	v_mfma_f32_16x16x32_bf16 v[64:67], v[184:187], v[220:223], v[64:67]
	s_barrier
	s_setprio 0
	s_add_i32 m0, s51, s41
	ds_read_b128 v[188:191], v158 offset:16384
	global_load_lds_dwordx4 v132, s[36:37]
	s_add_i32 m0, m0, 0x2000
	ds_read_b128 v[192:195], v158 offset:17408
	global_load_lds_dwordx4 v136, s[36:37]
	s_add_u32 s62, s36, 0x100000
	s_addc_u32 s63, s37, 0
	s_add_i32 m0, s52, s41
	ds_read_b128 v[196:199], v158 offset:18432
	global_load_lds_dwordx4 v132, s[62:63]
	s_add_i32 m0, m0, 0x2000
	ds_read_b128 v[200:203], v158 offset:19456
	global_load_lds_dwordx4 v136, s[62:63]
	s_mov_b32 m0, s29
	ds_read_b128 v[208:211], v158 offset:20480
	global_load_lds_dwordx4 v130, s[38:39]
	s_mov_b32 m0, s31
	ds_read_b128 v[212:215], v158 offset:21504
	global_load_lds_dwordx4 v134, s[38:39]
	ds_read_b128 v[216:219], v158 offset:22528
	ds_read_b128 v[220:223], v158 offset:23552
	s_waitcnt vmcnt(8) lgkmcnt(0)
	s_setprio 3
	s_barrier
	v_mfma_f32_16x16x32_bf16 v[60:63], v[148:151], v[188:191], v[60:63]
	v_mfma_f32_16x16x32_bf16 v[56:59], v[164:167], v[188:191], v[56:59]
	v_mfma_f32_16x16x32_bf16 v[44:47], v[148:151], v[196:199], v[44:47]
	v_mfma_f32_16x16x32_bf16 v[40:43], v[164:167], v[196:199], v[40:43]
	v_mfma_f32_16x16x32_bf16 v[28:31], v[148:151], v[208:211], v[28:31]
	v_mfma_f32_16x16x32_bf16 v[24:27], v[164:167], v[208:211], v[24:27]
	v_mfma_f32_16x16x32_bf16 v[12:15], v[148:151], v[216:219], v[12:15]
	v_mfma_f32_16x16x32_bf16 v[8:11], v[164:167], v[216:219], v[8:11]
	v_mfma_f32_16x16x32_bf16 v[60:63], v[160:163], v[192:195], v[60:63]
	v_mfma_f32_16x16x32_bf16 v[56:59], v[168:171], v[192:195], v[56:59]
	v_mfma_f32_16x16x32_bf16 v[44:47], v[160:163], v[200:203], v[44:47]
	v_mfma_f32_16x16x32_bf16 v[40:43], v[168:171], v[200:203], v[40:43]
	v_mfma_f32_16x16x32_bf16 v[28:31], v[160:163], v[212:215], v[28:31]
	v_mfma_f32_16x16x32_bf16 v[24:27], v[168:171], v[212:215], v[24:27]
	v_mfma_f32_16x16x32_bf16 v[12:15], v[160:163], v[220:223], v[12:15]
	v_mfma_f32_16x16x32_bf16 v[8:11], v[168:171], v[220:223], v[8:11]
	v_mfma_f32_16x16x32_bf16 v[52:55], v[172:175], v[188:191], v[52:55]
	v_mfma_f32_16x16x32_bf16 v[48:51], v[180:183], v[188:191], v[48:51]
	v_mfma_f32_16x16x32_bf16 v[36:39], v[172:175], v[196:199], v[36:39]
	v_mfma_f32_16x16x32_bf16 v[32:35], v[180:183], v[196:199], v[32:35]
	v_mfma_f32_16x16x32_bf16 v[20:23], v[172:175], v[208:211], v[20:23]
	v_mfma_f32_16x16x32_bf16 v[16:19], v[180:183], v[208:211], v[16:19]
	v_mfma_f32_16x16x32_bf16 v[4:7], v[172:175], v[216:219], v[4:7]
	v_mfma_f32_16x16x32_bf16 v[0:3], v[180:183], v[216:219], v[0:3]
	v_mfma_f32_16x16x32_bf16 v[52:55], v[176:179], v[192:195], v[52:55]
	v_mfma_f32_16x16x32_bf16 v[48:51], v[184:187], v[192:195], v[48:51]
	v_mfma_f32_16x16x32_bf16 v[36:39], v[176:179], v[200:203], v[36:39]
	v_mfma_f32_16x16x32_bf16 v[32:35], v[184:187], v[200:203], v[32:35]
	v_mfma_f32_16x16x32_bf16 v[20:23], v[176:179], v[212:215], v[20:23]
	v_mfma_f32_16x16x32_bf16 v[16:19], v[184:187], v[212:215], v[16:19]
	v_mfma_f32_16x16x32_bf16 v[4:7], v[176:179], v[220:223], v[4:7]
	v_mfma_f32_16x16x32_bf16 v[0:3], v[184:187], v[220:223], v[0:3]
	s_barrier
	s_setprio 0
	s_add_i32 s0, 0, 0x18000
	s_add_i32 s1, 0, 0x1c000
	ds_read_b128 v[148:151], v228
	ds_read_b128 v[160:163], v228 offset:1024
	ds_read_b128 v[164:167], v228 offset:2048
	ds_read_b128 v[168:171], v228 offset:3072
	ds_read_b128 v[172:175], v229
	ds_read_b128 v[176:179], v229 offset:1024
	ds_read_b128 v[180:183], v229 offset:2048
	ds_read_b128 v[184:187], v229 offset:3072
	s_add_u32 s38, s38, 0x100000
	s_addc_u32 s39, s39, 0
	s_mov_b32 m0, s42
	ds_read_b128 v[188:191], v158 offset:32768
	global_load_lds_dwordx4 v130, s[38:39]
	s_mov_b32 m0, s43
	ds_read_b128 v[192:195], v158 offset:33792
	global_load_lds_dwordx4 v134, s[38:39]
	ds_read_b128 v[196:199], v158 offset:34816
	ds_read_b128 v[200:203], v158 offset:35840
	ds_read_b128 v[208:211], v158 offset:36864
	ds_read_b128 v[212:215], v158 offset:37888
	ds_read_b128 v[216:219], v158 offset:38912
	ds_read_b128 v[220:223], v158 offset:39936
	s_waitcnt vmcnt(8) lgkmcnt(0)
	s_setprio 3
	s_barrier
	v_mfma_f32_16x16x32_bf16 v[124:127], v[148:151], v[188:191], v[124:127]
	v_mfma_f32_16x16x32_bf16 v[120:123], v[164:167], v[188:191], v[120:123]
	v_mfma_f32_16x16x32_bf16 v[108:111], v[148:151], v[196:199], v[108:111]
	v_mfma_f32_16x16x32_bf16 v[104:107], v[164:167], v[196:199], v[104:107]
	v_mfma_f32_16x16x32_bf16 v[92:95], v[148:151], v[208:211], v[92:95]
	v_mfma_f32_16x16x32_bf16 v[88:91], v[164:167], v[208:211], v[88:91]
	v_mfma_f32_16x16x32_bf16 v[76:79], v[148:151], v[216:219], v[76:79]
	v_mfma_f32_16x16x32_bf16 v[72:75], v[164:167], v[216:219], v[72:75]
	v_mfma_f32_16x16x32_bf16 v[124:127], v[160:163], v[192:195], v[124:127]
	v_mfma_f32_16x16x32_bf16 v[120:123], v[168:171], v[192:195], v[120:123]
	v_mfma_f32_16x16x32_bf16 v[108:111], v[160:163], v[200:203], v[108:111]
	v_mfma_f32_16x16x32_bf16 v[104:107], v[168:171], v[200:203], v[104:107]
	v_mfma_f32_16x16x32_bf16 v[92:95], v[160:163], v[212:215], v[92:95]
	v_mfma_f32_16x16x32_bf16 v[88:91], v[168:171], v[212:215], v[88:91]
	v_mfma_f32_16x16x32_bf16 v[76:79], v[160:163], v[220:223], v[76:79]
	v_mfma_f32_16x16x32_bf16 v[72:75], v[168:171], v[220:223], v[72:75]
	v_mfma_f32_16x16x32_bf16 v[116:119], v[172:175], v[188:191], v[116:119]
	v_mfma_f32_16x16x32_bf16 v[112:115], v[180:183], v[188:191], v[112:115]
	v_mfma_f32_16x16x32_bf16 v[100:103], v[172:175], v[196:199], v[100:103]
	v_mfma_f32_16x16x32_bf16 v[96:99], v[180:183], v[196:199], v[96:99]
	v_mfma_f32_16x16x32_bf16 v[84:87], v[172:175], v[208:211], v[84:87]
	v_mfma_f32_16x16x32_bf16 v[80:83], v[180:183], v[208:211], v[80:83]
	v_mfma_f32_16x16x32_bf16 v[68:71], v[172:175], v[216:219], v[68:71]
	v_mfma_f32_16x16x32_bf16 v[64:67], v[180:183], v[216:219], v[64:67]
	v_mfma_f32_16x16x32_bf16 v[116:119], v[176:179], v[192:195], v[116:119]
	v_mfma_f32_16x16x32_bf16 v[112:115], v[184:187], v[192:195], v[112:115]
	v_mfma_f32_16x16x32_bf16 v[100:103], v[176:179], v[200:203], v[100:103]
	v_mfma_f32_16x16x32_bf16 v[96:99], v[184:187], v[200:203], v[96:99]
	v_mfma_f32_16x16x32_bf16 v[84:87], v[176:179], v[212:215], v[84:87]
	v_mfma_f32_16x16x32_bf16 v[80:83], v[184:187], v[212:215], v[80:83]
	v_mfma_f32_16x16x32_bf16 v[68:71], v[176:179], v[220:223], v[68:71]
	v_mfma_f32_16x16x32_bf16 v[64:67], v[184:187], v[220:223], v[64:67]
	s_barrier
	s_setprio 0
	s_add_i32 s0, s0, s41
	s_add_u32 s100, s36, 0x80
	s_addc_u32 s101, s37, 0
	s_mov_b32 m0, s0
	ds_read_b128 v[188:191], v158 offset:49152
	global_load_lds_dwordx4 v132, s[100:101]
	s_add_i32 m0, s0, 0x2000
	ds_read_b128 v[192:195], v158 offset:50176
	global_load_lds_dwordx4 v136, s[100:101]
	s_add_u32 s36, s36, 0x100080
	s_addc_u32 s37, s37, 0
	s_add_i32 m0, s1, s41
	ds_read_b128 v[196:199], v158 offset:51200
	global_load_lds_dwordx4 v132, s[36:37]
	s_add_i32 m0, m0, 0x2000
	ds_read_b128 v[200:203], v158 offset:52224
	global_load_lds_dwordx4 v136, s[36:37]
	s_add_u32 s100, s38, 0xfff00080
	s_addc_u32 s101, s39, -1
	s_mov_b32 m0, s46
	ds_read_b128 v[208:211], v158 offset:53248
	global_load_lds_dwordx4 v130, s[100:101]
	s_mov_b32 m0, s47
	ds_read_b128 v[212:215], v158 offset:54272
	global_load_lds_dwordx4 v134, s[100:101]
	ds_read_b128 v[216:219], v158 offset:55296
	ds_read_b128 v[220:223], v158 offset:56320
	s_waitcnt vmcnt(8) lgkmcnt(0)
	s_setprio 3
	s_barrier
	v_mfma_f32_16x16x32_bf16 v[60:63], v[148:151], v[188:191], v[60:63]
	v_mfma_f32_16x16x32_bf16 v[56:59], v[164:167], v[188:191], v[56:59]
	v_mfma_f32_16x16x32_bf16 v[44:47], v[148:151], v[196:199], v[44:47]
	v_mfma_f32_16x16x32_bf16 v[40:43], v[164:167], v[196:199], v[40:43]
	v_mfma_f32_16x16x32_bf16 v[28:31], v[148:151], v[208:211], v[28:31]
	v_mfma_f32_16x16x32_bf16 v[24:27], v[164:167], v[208:211], v[24:27]
	v_mfma_f32_16x16x32_bf16 v[12:15], v[148:151], v[216:219], v[12:15]
	v_mfma_f32_16x16x32_bf16 v[8:11], v[164:167], v[216:219], v[8:11]
	v_mfma_f32_16x16x32_bf16 v[60:63], v[160:163], v[192:195], v[60:63]
	v_mfma_f32_16x16x32_bf16 v[56:59], v[168:171], v[192:195], v[56:59]
	v_mfma_f32_16x16x32_bf16 v[44:47], v[160:163], v[200:203], v[44:47]
	v_mfma_f32_16x16x32_bf16 v[40:43], v[168:171], v[200:203], v[40:43]
	v_mfma_f32_16x16x32_bf16 v[28:31], v[160:163], v[212:215], v[28:31]
	v_mfma_f32_16x16x32_bf16 v[24:27], v[168:171], v[212:215], v[24:27]
	v_mfma_f32_16x16x32_bf16 v[12:15], v[160:163], v[220:223], v[12:15]
	v_mfma_f32_16x16x32_bf16 v[8:11], v[168:171], v[220:223], v[8:11]
	s_add_u32 s34, s34, 0x100
	s_addc_u32 s35, s35, 0
	s_add_i32 s60, s60, 2
	s_add_u32 s58, s58, 0x100
	s_addc_u32 s59, s59, 0
	v_mfma_f32_16x16x32_bf16 v[52:55], v[172:175], v[188:191], v[52:55]
	v_mfma_f32_16x16x32_bf16 v[48:51], v[180:183], v[188:191], v[48:51]
	v_mfma_f32_16x16x32_bf16 v[36:39], v[172:175], v[196:199], v[36:39]
	v_mfma_f32_16x16x32_bf16 v[32:35], v[180:183], v[196:199], v[32:35]
	v_mfma_f32_16x16x32_bf16 v[20:23], v[172:175], v[208:211], v[20:23]
	v_mfma_f32_16x16x32_bf16 v[16:19], v[180:183], v[208:211], v[16:19]
	v_mfma_f32_16x16x32_bf16 v[4:7], v[172:175], v[216:219], v[4:7]
	v_mfma_f32_16x16x32_bf16 v[0:3], v[180:183], v[216:219], v[0:3]
	v_mfma_f32_16x16x32_bf16 v[52:55], v[176:179], v[192:195], v[52:55]
	v_mfma_f32_16x16x32_bf16 v[48:51], v[184:187], v[192:195], v[48:51]
	v_mfma_f32_16x16x32_bf16 v[36:39], v[176:179], v[200:203], v[36:39]
	v_mfma_f32_16x16x32_bf16 v[32:35], v[184:187], v[200:203], v[32:35]
	v_mfma_f32_16x16x32_bf16 v[20:23], v[176:179], v[212:215], v[20:23]
	v_mfma_f32_16x16x32_bf16 v[16:19], v[184:187], v[212:215], v[16:19]
	v_mfma_f32_16x16x32_bf16 v[4:7], v[176:179], v[220:223], v[4:7]
	v_mfma_f32_16x16x32_bf16 v[0:3], v[184:187], v[220:223], v[0:3]
	s_barrier
	s_setprio 0
	s_cmp_gt_u32 s60, 61
	s_cbranch_scc0 .LBB0_134
	s_and_b64 vcc, exec, s[10:11]
	s_cbranch_vccz .LBB0_137
	s_barrier

.LBB0_677:
	ds_read_b128 v[156:159], v152
	ds_read_b128 v[160:163], v152 offset:1024
	ds_read_b128 v[164:167], v152 offset:2048
	ds_read_b128 v[168:171], v152 offset:3072
	ds_read_b128 v[172:175], v153
	ds_read_b128 v[176:179], v153 offset:1024
	ds_read_b128 v[180:183], v153 offset:2048
	ds_read_b128 v[184:187], v153 offset:3072
	s_add_u32 s0, s36, 0xfff00080
	s_addc_u32 s1, s37, -1
	s_cmp_eq_u32 s61, 60
	s_cselect_b32 s41, s56, s1
	s_cselect_b32 s40, s57, s0
	s_cselect_b32 s39, s15, s60
	s_cselect_b32 s38, s58, s59
	s_add_i32 m0, s31, 0xc000
	ds_read_b128 v[188:191], v154
	ds_read_b128 v[192:195], v154 offset:1024
	ds_read_b128 v[196:199], v154 offset:2048
	ds_read_b128 v[200:203], v154 offset:3072
	ds_read_b128 v[204:207], v154 offset:4096
	ds_read_b128 v[208:211], v154 offset:5120
	ds_read_b128 v[212:215], v154 offset:6144
	global_load_lds_dwordx4 v138, s[36:37]
	s_add_i32 m0, s31, 0xe000
	ds_read_b128 v[216:219], v154 offset:7168
	global_load_lds_dwordx4 v140, s[36:37]
	s_waitcnt vmcnt(8) lgkmcnt(0)
	s_setprio 3
	s_barrier
	v_mfma_f32_16x16x32_bf16 v[124:127], v[156:159], v[188:191], v[124:127]
	v_mfma_f32_16x16x32_bf16 v[120:123], v[164:167], v[188:191], v[120:123]
	v_mfma_f32_16x16x32_bf16 v[108:111], v[156:159], v[196:199], v[108:111]
	v_mfma_f32_16x16x32_bf16 v[104:107], v[164:167], v[196:199], v[104:107]
	v_mfma_f32_16x16x32_bf16 v[92:95], v[156:159], v[204:207], v[92:95]
	v_mfma_f32_16x16x32_bf16 v[88:91], v[164:167], v[204:207], v[88:91]
	v_mfma_f32_16x16x32_bf16 v[76:79], v[156:159], v[212:215], v[76:79]
	v_mfma_f32_16x16x32_bf16 v[72:75], v[164:167], v[212:215], v[72:75]
	v_mfma_f32_16x16x32_bf16 v[124:127], v[160:163], v[192:195], v[124:127]
	v_mfma_f32_16x16x32_bf16 v[120:123], v[168:171], v[192:195], v[120:123]
	v_mfma_f32_16x16x32_bf16 v[108:111], v[160:163], v[200:203], v[108:111]
	v_mfma_f32_16x16x32_bf16 v[104:107], v[168:171], v[200:203], v[104:107]
	v_mfma_f32_16x16x32_bf16 v[92:95], v[160:163], v[208:211], v[92:95]
	v_mfma_f32_16x16x32_bf16 v[88:91], v[168:171], v[208:211], v[88:91]
	v_mfma_f32_16x16x32_bf16 v[76:79], v[160:163], v[216:219], v[76:79]
	v_mfma_f32_16x16x32_bf16 v[72:75], v[168:171], v[216:219], v[72:75]
	v_mfma_f32_16x16x32_bf16 v[116:119], v[172:175], v[188:191], v[116:119]
	v_mfma_f32_16x16x32_bf16 v[112:115], v[180:183], v[188:191], v[112:115]
	v_mfma_f32_16x16x32_bf16 v[100:103], v[172:175], v[196:199], v[100:103]
	v_mfma_f32_16x16x32_bf16 v[96:99], v[180:183], v[196:199], v[96:99]
	v_mfma_f32_16x16x32_bf16 v[84:87], v[172:175], v[204:207], v[84:87]
	v_mfma_f32_16x16x32_bf16 v[80:83], v[180:183], v[204:207], v[80:83]
	v_mfma_f32_16x16x32_bf16 v[68:71], v[172:175], v[212:215], v[68:71]
	v_mfma_f32_16x16x32_bf16 v[64:67], v[180:183], v[212:215], v[64:67]
	v_mfma_f32_16x16x32_bf16 v[116:119], v[176:179], v[192:195], v[116:119]
	v_mfma_f32_16x16x32_bf16 v[112:115], v[184:187], v[192:195], v[112:115]
	v_mfma_f32_16x16x32_bf16 v[100:103], v[176:179], v[200:203], v[100:103]
	v_mfma_f32_16x16x32_bf16 v[96:99], v[184:187], v[200:203], v[96:99]
	v_mfma_f32_16x16x32_bf16 v[84:87], v[176:179], v[208:211], v[84:87]
	v_mfma_f32_16x16x32_bf16 v[80:83], v[184:187], v[208:211], v[80:83]
	v_mfma_f32_16x16x32_bf16 v[68:71], v[176:179], v[216:219], v[68:71]
	v_mfma_f32_16x16x32_bf16 v[64:67], v[184:187], v[216:219], v[64:67]
	s_barrier
	s_setprio 0
	s_add_i32 m0, s51, s43
	ds_read_b128 v[188:191], v154 offset:16384
	ds_read_b128 v[192:195], v154 offset:17408
	ds_read_b128 v[196:199], v154 offset:18432
	ds_read_b128 v[200:203], v154 offset:19456
	ds_read_b128 v[204:207], v154 offset:20480
	global_load_lds_dwordx4 v130, s[38:39]
	s_add_i32 m0, m0, 0x2000
	s_add_u32 s0, s38, 0x100000
	s_addc_u32 s1, s39, 0
	s_add_i32 s62, s52, s43
	global_load_lds_dwordx4 v134, s[38:39]
	s_mov_b32 m0, s62
	s_nop 0
	global_load_lds_dwordx4 v130, s[0:1]
	s_add_i32 m0, s62, 0x2000
	ds_read_b128 v[216:219], v154 offset:23552
	global_load_lds_dwordx4 v134, s[0:1]
	s_mov_b32 m0, s31
	ds_read_b128 v[212:215], v154 offset:22528
	global_load_lds_dwordx4 v128, s[40:41]
	s_mov_b32 m0, s35
	ds_read_b128 v[208:211], v154 offset:21504
	global_load_lds_dwordx4 v132, s[40:41]
	s_waitcnt vmcnt(8) lgkmcnt(0)
	s_setprio 3
	s_barrier
	v_mfma_f32_16x16x32_bf16 v[60:63], v[156:159], v[188:191], v[60:63]
	v_mfma_f32_16x16x32_bf16 v[56:59], v[164:167], v[188:191], v[56:59]
	v_mfma_f32_16x16x32_bf16 v[44:47], v[156:159], v[196:199], v[44:47]
	v_mfma_f32_16x16x32_bf16 v[40:43], v[164:167], v[196:199], v[40:43]
	v_mfma_f32_16x16x32_bf16 v[28:31], v[156:159], v[204:207], v[28:31]
	v_mfma_f32_16x16x32_bf16 v[24:27], v[164:167], v[204:207], v[24:27]
	v_mfma_f32_16x16x32_bf16 v[12:15], v[156:159], v[212:215], v[12:15]
	v_mfma_f32_16x16x32_bf16 v[8:11], v[164:167], v[212:215], v[8:11]
	v_mfma_f32_16x16x32_bf16 v[60:63], v[160:163], v[192:195], v[60:63]
	v_mfma_f32_16x16x32_bf16 v[56:59], v[168:171], v[192:195], v[56:59]
	v_mfma_f32_16x16x32_bf16 v[44:47], v[160:163], v[200:203], v[44:47]
	v_mfma_f32_16x16x32_bf16 v[40:43], v[168:171], v[200:203], v[40:43]
	v_mfma_f32_16x16x32_bf16 v[28:31], v[160:163], v[208:211], v[28:31]
	v_mfma_f32_16x16x32_bf16 v[24:27], v[168:171], v[208:211], v[24:27]
	v_mfma_f32_16x16x32_bf16 v[12:15], v[160:163], v[216:219], v[12:15]
	v_mfma_f32_16x16x32_bf16 v[8:11], v[168:171], v[216:219], v[8:11]
	v_mfma_f32_16x16x32_bf16 v[52:55], v[172:175], v[188:191], v[52:55]
	v_mfma_f32_16x16x32_bf16 v[48:51], v[180:183], v[188:191], v[48:51]
	v_mfma_f32_16x16x32_bf16 v[36:39], v[172:175], v[196:199], v[36:39]
	v_mfma_f32_16x16x32_bf16 v[32:35], v[180:183], v[196:199], v[32:35]
	v_mfma_f32_16x16x32_bf16 v[20:23], v[172:175], v[204:207], v[20:23]
	v_mfma_f32_16x16x32_bf16 v[16:19], v[180:183], v[204:207], v[16:19]
	v_mfma_f32_16x16x32_bf16 v[4:7], v[172:175], v[212:215], v[4:7]
	v_mfma_f32_16x16x32_bf16 v[0:3], v[180:183], v[212:215], v[0:3]
	v_mfma_f32_16x16x32_bf16 v[52:55], v[176:179], v[192:195], v[52:55]
	v_mfma_f32_16x16x32_bf16 v[48:51], v[184:187], v[192:195], v[48:51]
	v_mfma_f32_16x16x32_bf16 v[36:39], v[176:179], v[200:203], v[36:39]
	v_mfma_f32_16x16x32_bf16 v[32:35], v[184:187], v[200:203], v[32:35]
	v_mfma_f32_16x16x32_bf16 v[20:23], v[176:179], v[208:211], v[20:23]
	v_mfma_f32_16x16x32_bf16 v[16:19], v[184:187], v[208:211], v[16:19]
	v_mfma_f32_16x16x32_bf16 v[4:7], v[176:179], v[216:219], v[4:7]
	v_mfma_f32_16x16x32_bf16 v[0:3], v[184:187], v[216:219], v[0:3]
	s_barrier
	s_setprio 0
	s_add_i32 s62, 0, 0x18000
	s_add_i32 s63, 0, 0x1c000
	ds_read_b128 v[156:159], v226
	ds_read_b128 v[160:163], v226 offset:1024
	ds_read_b128 v[164:167], v226 offset:2048
	ds_read_b128 v[168:171], v226 offset:3072
	ds_read_b128 v[172:175], v227
	ds_read_b128 v[176:179], v227 offset:1024
	ds_read_b128 v[180:183], v227 offset:2048
	ds_read_b128 v[184:187], v227 offset:3072
	s_add_u32 s0, s40, 0x100000
	s_addc_u32 s1, s41, 0
	s_mov_b32 m0, s44
	ds_read_b128 v[188:191], v154 offset:32768
	ds_read_b128 v[192:195], v154 offset:33792
	ds_read_b128 v[196:199], v154 offset:34816
	ds_read_b128 v[200:203], v154 offset:35840
	ds_read_b128 v[204:207], v154 offset:36864
	ds_read_b128 v[208:211], v154 offset:37888
	ds_read_b128 v[212:215], v154 offset:38912
	global_load_lds_dwordx4 v128, s[0:1]
	s_mov_b32 m0, s45
	ds_read_b128 v[216:219], v154 offset:39936
	global_load_lds_dwordx4 v132, s[0:1]
	s_waitcnt vmcnt(8) lgkmcnt(0)
	s_setprio 3
	s_barrier
	v_mfma_f32_16x16x32_bf16 v[124:127], v[156:159], v[188:191], v[124:127]
	v_mfma_f32_16x16x32_bf16 v[120:123], v[164:167], v[188:191], v[120:123]
	v_mfma_f32_16x16x32_bf16 v[108:111], v[156:159], v[196:199], v[108:111]
	v_mfma_f32_16x16x32_bf16 v[104:107], v[164:167], v[196:199], v[104:107]
	v_mfma_f32_16x16x32_bf16 v[92:95], v[156:159], v[204:207], v[92:95]
	v_mfma_f32_16x16x32_bf16 v[88:91], v[164:167], v[204:207], v[88:91]
	v_mfma_f32_16x16x32_bf16 v[76:79], v[156:159], v[212:215], v[76:79]
	v_mfma_f32_16x16x32_bf16 v[72:75], v[164:167], v[212:215], v[72:75]
	v_mfma_f32_16x16x32_bf16 v[124:127], v[160:163], v[192:195], v[124:127]
	v_mfma_f32_16x16x32_bf16 v[120:123], v[168:171], v[192:195], v[120:123]
	v_mfma_f32_16x16x32_bf16 v[108:111], v[160:163], v[200:203], v[108:111]
	v_mfma_f32_16x16x32_bf16 v[104:107], v[168:171], v[200:203], v[104:107]
	v_mfma_f32_16x16x32_bf16 v[92:95], v[160:163], v[208:211], v[92:95]
	v_mfma_f32_16x16x32_bf16 v[88:91], v[168:171], v[208:211], v[88:91]
	v_mfma_f32_16x16x32_bf16 v[76:79], v[160:163], v[216:219], v[76:79]
	v_mfma_f32_16x16x32_bf16 v[72:75], v[168:171], v[216:219], v[72:75]
	v_mfma_f32_16x16x32_bf16 v[116:119], v[172:175], v[188:191], v[116:119]
	v_mfma_f32_16x16x32_bf16 v[112:115], v[180:183], v[188:191], v[112:115]
	v_mfma_f32_16x16x32_bf16 v[100:103], v[172:175], v[196:199], v[100:103]
	v_mfma_f32_16x16x32_bf16 v[96:99], v[180:183], v[196:199], v[96:99]
	v_mfma_f32_16x16x32_bf16 v[84:87], v[172:175], v[204:207], v[84:87]
	v_mfma_f32_16x16x32_bf16 v[80:83], v[180:183], v[204:207], v[80:83]
	v_mfma_f32_16x16x32_bf16 v[68:71], v[172:175], v[212:215], v[68:71]
	v_mfma_f32_16x16x32_bf16 v[64:67], v[180:183], v[212:215], v[64:67]
	v_mfma_f32_16x16x32_bf16 v[116:119], v[176:179], v[192:195], v[116:119]
	v_mfma_f32_16x16x32_bf16 v[112:115], v[184:187], v[192:195], v[112:115]
	v_mfma_f32_16x16x32_bf16 v[100:103], v[176:179], v[200:203], v[100:103]
	v_mfma_f32_16x16x32_bf16 v[96:99], v[184:187], v[200:203], v[96:99]
	v_mfma_f32_16x16x32_bf16 v[84:87], v[176:179], v[208:211], v[84:87]
	v_mfma_f32_16x16x32_bf16 v[80:83], v[184:187], v[208:211], v[80:83]
	v_mfma_f32_16x16x32_bf16 v[68:71], v[176:179], v[216:219], v[68:71]
	v_mfma_f32_16x16x32_bf16 v[64:67], v[184:187], v[216:219], v[64:67]
	s_barrier
	s_setprio 0
	s_add_u32 s100, s38, 0x80
	s_addc_u32 s101, s39, 0
	s_add_i32 m0, s62, s43
	ds_read_b128 v[188:191], v154 offset:49152
	ds_read_b128 v[192:195], v154 offset:50176
	ds_read_b128 v[196:199], v154 offset:51200
	ds_read_b128 v[200:203], v154 offset:52224
	global_load_lds_dwordx4 v130, s[100:101]
	s_add_i32 m0, m0, 0x2000
	s_add_u32 s0, s38, 0x100080
	s_addc_u32 s1, s39, 0
	s_add_i32 s38, s63, s43
	global_load_lds_dwordx4 v134, s[100:101]
	s_mov_b32 m0, s38
	ds_read_b128 v[216:219], v154 offset:56320
	global_load_lds_dwordx4 v130, s[0:1]
	s_add_i32 m0, s38, 0x2000
	ds_read_b128 v[212:215], v154 offset:55296
	global_load_lds_dwordx4 v134, s[0:1]
	s_add_u32 s100, s40, 0x80
	s_addc_u32 s101, s41, 0
	s_mov_b32 m0, s46
	ds_read_b128 v[208:211], v154 offset:54272
	global_load_lds_dwordx4 v128, s[100:101]
	s_mov_b32 m0, s47
	ds_read_b128 v[204:207], v154 offset:53248
	global_load_lds_dwordx4 v132, s[100:101]
	s_waitcnt vmcnt(8) lgkmcnt(0)
	s_setprio 3
	s_barrier
	v_mfma_f32_16x16x32_bf16 v[60:63], v[156:159], v[188:191], v[60:63]
	v_mfma_f32_16x16x32_bf16 v[56:59], v[164:167], v[188:191], v[56:59]
	v_mfma_f32_16x16x32_bf16 v[44:47], v[156:159], v[196:199], v[44:47]
	v_mfma_f32_16x16x32_bf16 v[40:43], v[164:167], v[196:199], v[40:43]
	v_mfma_f32_16x16x32_bf16 v[28:31], v[156:159], v[204:207], v[28:31]
	v_mfma_f32_16x16x32_bf16 v[24:27], v[164:167], v[204:207], v[24:27]
	v_mfma_f32_16x16x32_bf16 v[12:15], v[156:159], v[212:215], v[12:15]
	v_mfma_f32_16x16x32_bf16 v[8:11], v[164:167], v[212:215], v[8:11]
	v_mfma_f32_16x16x32_bf16 v[60:63], v[160:163], v[192:195], v[60:63]
	v_mfma_f32_16x16x32_bf16 v[56:59], v[168:171], v[192:195], v[56:59]
	v_mfma_f32_16x16x32_bf16 v[44:47], v[160:163], v[200:203], v[44:47]
	v_mfma_f32_16x16x32_bf16 v[40:43], v[168:171], v[200:203], v[40:43]
	v_mfma_f32_16x16x32_bf16 v[28:31], v[160:163], v[208:211], v[28:31]
	v_mfma_f32_16x16x32_bf16 v[24:27], v[168:171], v[208:211], v[24:27]
	v_mfma_f32_16x16x32_bf16 v[12:15], v[160:163], v[216:219], v[12:15]
	v_mfma_f32_16x16x32_bf16 v[8:11], v[168:171], v[216:219], v[8:11]
	s_add_u32 s36, s36, 0x100
	s_addc_u32 s37, s37, 0
	s_add_i32 s61, s61, 2
	s_add_u32 s59, s59, 0x100
	s_addc_u32 s60, s60, 0
	v_mfma_f32_16x16x32_bf16 v[52:55], v[172:175], v[188:191], v[52:55]
	v_mfma_f32_16x16x32_bf16 v[48:51], v[180:183], v[188:191], v[48:51]
	v_mfma_f32_16x16x32_bf16 v[36:39], v[172:175], v[196:199], v[36:39]
	v_mfma_f32_16x16x32_bf16 v[32:35], v[180:183], v[196:199], v[32:35]
	v_mfma_f32_16x16x32_bf16 v[20:23], v[172:175], v[204:207], v[20:23]
	v_mfma_f32_16x16x32_bf16 v[16:19], v[180:183], v[204:207], v[16:19]
	v_mfma_f32_16x16x32_bf16 v[4:7], v[172:175], v[212:215], v[4:7]
	v_mfma_f32_16x16x32_bf16 v[0:3], v[180:183], v[212:215], v[0:3]
	v_mfma_f32_16x16x32_bf16 v[52:55], v[176:179], v[192:195], v[52:55]
	v_mfma_f32_16x16x32_bf16 v[48:51], v[184:187], v[192:195], v[48:51]
	v_mfma_f32_16x16x32_bf16 v[36:39], v[176:179], v[200:203], v[36:39]
	v_mfma_f32_16x16x32_bf16 v[32:35], v[184:187], v[200:203], v[32:35]
	v_mfma_f32_16x16x32_bf16 v[20:23], v[176:179], v[208:211], v[20:23]
	v_mfma_f32_16x16x32_bf16 v[16:19], v[184:187], v[208:211], v[16:19]
	v_mfma_f32_16x16x32_bf16 v[4:7], v[176:179], v[216:219], v[4:7]
	v_mfma_f32_16x16x32_bf16 v[0:3], v[184:187], v[216:219], v[0:3]
	s_barrier
	s_setprio 0
	s_cmp_gt_u32 s61, 61
	s_cbranch_scc0 .LBB0_677
	s_and_b64 vcc, exec, s[12:13]
	s_cbranch_vccz .LBB0_680
	s_barrier

.LBB0_1637:
	ds_read_b128 v[152:155], v149
	ds_read_b128 v[156:159], v149 offset:1024
	ds_read_b128 v[160:163], v149 offset:2048
	ds_read_b128 v[164:167], v149 offset:3072
	ds_read_b128 v[168:171], v150
	ds_read_b128 v[172:175], v150 offset:1024
	ds_read_b128 v[176:179], v150 offset:2048
	ds_read_b128 v[180:183], v150 offset:3072
	s_add_u32 s0, s42, 0xfff00080
	s_addc_u32 s1, s43, -1
	s_cmp_eq_u32 s68, 60
	s_cselect_b32 s47, s35, s1
	s_cselect_b32 s46, s64, s0
	s_cselect_b32 s45, s31, s67
	s_cselect_b32 s44, s65, s66
	s_add_i32 m0, s41, 0xc000
	ds_read_b128 v[184:187], v151
	ds_read_b128 v[188:191], v151 offset:1024
	ds_read_b128 v[192:195], v151 offset:2048
	ds_read_b128 v[196:199], v151 offset:3072
	ds_read_b128 v[200:203], v151 offset:4096
	ds_read_b128 v[210:213], v151 offset:5120
	ds_read_b128 v[214:217], v151 offset:6144
	global_load_lds_dwordx4 v136, s[42:43]
	s_add_i32 m0, s41, 0xe000
	ds_read_b128 v[218:221], v151 offset:7168
	global_load_lds_dwordx4 v138, s[42:43]
	s_waitcnt vmcnt(8) lgkmcnt(0)
	s_setprio 3
	s_barrier
	v_mfma_f32_16x16x32_bf16 v[124:127], v[152:155], v[184:187], v[124:127]
	v_mfma_f32_16x16x32_bf16 v[120:123], v[160:163], v[184:187], v[120:123]
	v_mfma_f32_16x16x32_bf16 v[116:119], v[152:155], v[192:195], v[116:119]
	v_mfma_f32_16x16x32_bf16 v[108:111], v[160:163], v[192:195], v[108:111]
	v_mfma_f32_16x16x32_bf16 v[100:103], v[152:155], v[200:203], v[100:103]
	v_mfma_f32_16x16x32_bf16 v[92:95], v[160:163], v[200:203], v[92:95]
	v_mfma_f32_16x16x32_bf16 v[84:87], v[152:155], v[214:217], v[84:87]
	v_mfma_f32_16x16x32_bf16 v[76:79], v[160:163], v[214:217], v[76:79]
	v_mfma_f32_16x16x32_bf16 v[124:127], v[156:159], v[188:191], v[124:127]
	v_mfma_f32_16x16x32_bf16 v[120:123], v[164:167], v[188:191], v[120:123]
	v_mfma_f32_16x16x32_bf16 v[116:119], v[156:159], v[196:199], v[116:119]
	v_mfma_f32_16x16x32_bf16 v[108:111], v[164:167], v[196:199], v[108:111]
	v_mfma_f32_16x16x32_bf16 v[100:103], v[156:159], v[210:213], v[100:103]
	v_mfma_f32_16x16x32_bf16 v[92:95], v[164:167], v[210:213], v[92:95]
	v_mfma_f32_16x16x32_bf16 v[84:87], v[156:159], v[218:221], v[84:87]
	v_mfma_f32_16x16x32_bf16 v[76:79], v[164:167], v[218:221], v[76:79]
	v_mfma_f32_16x16x32_bf16 v[112:115], v[168:171], v[184:187], v[112:115]
	v_mfma_f32_16x16x32_bf16 v[104:107], v[176:179], v[184:187], v[104:107]
	v_mfma_f32_16x16x32_bf16 v[96:99], v[168:171], v[192:195], v[96:99]
	v_mfma_f32_16x16x32_bf16 v[88:91], v[176:179], v[192:195], v[88:91]
	v_mfma_f32_16x16x32_bf16 v[80:83], v[168:171], v[200:203], v[80:83]
	v_mfma_f32_16x16x32_bf16 v[72:75], v[176:179], v[200:203], v[72:75]
	v_mfma_f32_16x16x32_bf16 v[68:71], v[168:171], v[214:217], v[68:71]
	v_mfma_f32_16x16x32_bf16 v[64:67], v[176:179], v[214:217], v[64:67]
	v_mfma_f32_16x16x32_bf16 v[112:115], v[172:175], v[188:191], v[112:115]
	v_mfma_f32_16x16x32_bf16 v[104:107], v[180:183], v[188:191], v[104:107]
	v_mfma_f32_16x16x32_bf16 v[96:99], v[172:175], v[196:199], v[96:99]
	v_mfma_f32_16x16x32_bf16 v[88:91], v[180:183], v[196:199], v[88:91]
	v_mfma_f32_16x16x32_bf16 v[80:83], v[172:175], v[210:213], v[80:83]
	v_mfma_f32_16x16x32_bf16 v[72:75], v[180:183], v[210:213], v[72:75]
	v_mfma_f32_16x16x32_bf16 v[68:71], v[172:175], v[218:221], v[68:71]
	v_mfma_f32_16x16x32_bf16 v[64:67], v[180:183], v[218:221], v[64:67]
	s_barrier
	s_setprio 0
	s_add_i32 m0, s57, s49
	ds_read_b128 v[184:187], v151 offset:16384
	ds_read_b128 v[188:191], v151 offset:17408
	ds_read_b128 v[192:195], v151 offset:18432
	ds_read_b128 v[196:199], v151 offset:19456
	ds_read_b128 v[200:203], v151 offset:20480
	global_load_lds_dwordx4 v130, s[44:45]
	s_add_i32 m0, m0, 0x2000
	s_add_u32 s0, s44, 0x100000
	s_addc_u32 s1, s45, 0
	s_add_i32 s69, s58, s49
	global_load_lds_dwordx4 v134, s[44:45]
	s_mov_b32 m0, s69
	s_nop 0
	global_load_lds_dwordx4 v130, s[0:1]
	s_add_i32 m0, s69, 0x2000
	ds_read_b128 v[218:221], v151 offset:23552
	global_load_lds_dwordx4 v134, s[0:1]
	s_mov_b32 m0, s41
	ds_read_b128 v[214:217], v151 offset:22528
	global_load_lds_dwordx4 v128, s[46:47]
	s_mov_b32 m0, s50
	ds_read_b128 v[210:213], v151 offset:21504
	global_load_lds_dwordx4 v132, s[46:47]
	s_waitcnt vmcnt(8) lgkmcnt(0)
	s_setprio 3
	s_barrier
	v_mfma_f32_16x16x32_bf16 v[60:63], v[152:155], v[184:187], v[60:63]
	v_mfma_f32_16x16x32_bf16 v[56:59], v[160:163], v[184:187], v[56:59]
	v_mfma_f32_16x16x32_bf16 v[52:55], v[152:155], v[192:195], v[52:55]
	v_mfma_f32_16x16x32_bf16 v[44:47], v[160:163], v[192:195], v[44:47]
	v_mfma_f32_16x16x32_bf16 v[36:39], v[152:155], v[200:203], v[36:39]
	v_mfma_f32_16x16x32_bf16 v[28:31], v[160:163], v[200:203], v[28:31]
	v_mfma_f32_16x16x32_bf16 v[20:23], v[152:155], v[214:217], v[20:23]
	v_mfma_f32_16x16x32_bf16 v[12:15], v[160:163], v[214:217], v[12:15]
	v_mfma_f32_16x16x32_bf16 v[60:63], v[156:159], v[188:191], v[60:63]
	v_mfma_f32_16x16x32_bf16 v[56:59], v[164:167], v[188:191], v[56:59]
	v_mfma_f32_16x16x32_bf16 v[52:55], v[156:159], v[196:199], v[52:55]
	v_mfma_f32_16x16x32_bf16 v[44:47], v[164:167], v[196:199], v[44:47]
	v_mfma_f32_16x16x32_bf16 v[36:39], v[156:159], v[210:213], v[36:39]
	v_mfma_f32_16x16x32_bf16 v[28:31], v[164:167], v[210:213], v[28:31]
	v_mfma_f32_16x16x32_bf16 v[20:23], v[156:159], v[218:221], v[20:23]
	v_mfma_f32_16x16x32_bf16 v[12:15], v[164:167], v[218:221], v[12:15]
	v_mfma_f32_16x16x32_bf16 v[48:51], v[168:171], v[184:187], v[48:51]
	v_mfma_f32_16x16x32_bf16 v[40:43], v[176:179], v[184:187], v[40:43]
	v_mfma_f32_16x16x32_bf16 v[32:35], v[168:171], v[192:195], v[32:35]
	v_mfma_f32_16x16x32_bf16 v[24:27], v[176:179], v[192:195], v[24:27]
	v_mfma_f32_16x16x32_bf16 v[16:19], v[168:171], v[200:203], v[16:19]
	v_mfma_f32_16x16x32_bf16 v[8:11], v[176:179], v[200:203], v[8:11]
	v_mfma_f32_16x16x32_bf16 v[4:7], v[168:171], v[214:217], v[4:7]
	v_mfma_f32_16x16x32_bf16 v[0:3], v[176:179], v[214:217], v[0:3]
	v_mfma_f32_16x16x32_bf16 v[48:51], v[172:175], v[188:191], v[48:51]
	v_mfma_f32_16x16x32_bf16 v[40:43], v[180:183], v[188:191], v[40:43]
	v_mfma_f32_16x16x32_bf16 v[32:35], v[172:175], v[196:199], v[32:35]
	v_mfma_f32_16x16x32_bf16 v[24:27], v[180:183], v[196:199], v[24:27]
	v_mfma_f32_16x16x32_bf16 v[16:19], v[172:175], v[210:213], v[16:19]
	v_mfma_f32_16x16x32_bf16 v[8:11], v[180:183], v[210:213], v[8:11]
	v_mfma_f32_16x16x32_bf16 v[4:7], v[172:175], v[218:221], v[4:7]
	v_mfma_f32_16x16x32_bf16 v[0:3], v[180:183], v[218:221], v[0:3]
	s_barrier
	s_setprio 0
	s_add_i32 s69, 0, 0x18000
	s_add_i32 s70, 0, 0x1c000
	ds_read_b128 v[152:155], v228
	ds_read_b128 v[156:159], v228 offset:1024
	ds_read_b128 v[160:163], v228 offset:2048
	ds_read_b128 v[164:167], v228 offset:3072
	ds_read_b128 v[168:171], v229
	ds_read_b128 v[172:175], v229 offset:1024
	ds_read_b128 v[176:179], v229 offset:2048
	ds_read_b128 v[180:183], v229 offset:3072
	s_add_u32 s0, s46, 0x100000
	s_addc_u32 s1, s47, 0
	s_mov_b32 m0, s51
	ds_read_b128 v[184:187], v151 offset:32768
	ds_read_b128 v[188:191], v151 offset:33792
	ds_read_b128 v[192:195], v151 offset:34816
	ds_read_b128 v[196:199], v151 offset:35840
	ds_read_b128 v[200:203], v151 offset:36864
	ds_read_b128 v[210:213], v151 offset:37888
	ds_read_b128 v[214:217], v151 offset:38912
	global_load_lds_dwordx4 v128, s[0:1]
	s_mov_b32 m0, s52
	ds_read_b128 v[218:221], v151 offset:39936
	global_load_lds_dwordx4 v132, s[0:1]
	s_waitcnt vmcnt(8) lgkmcnt(0)
	s_setprio 3
	s_barrier
	v_mfma_f32_16x16x32_bf16 v[124:127], v[152:155], v[184:187], v[124:127]
	v_mfma_f32_16x16x32_bf16 v[120:123], v[160:163], v[184:187], v[120:123]
	v_mfma_f32_16x16x32_bf16 v[116:119], v[152:155], v[192:195], v[116:119]
	v_mfma_f32_16x16x32_bf16 v[108:111], v[160:163], v[192:195], v[108:111]
	v_mfma_f32_16x16x32_bf16 v[100:103], v[152:155], v[200:203], v[100:103]
	v_mfma_f32_16x16x32_bf16 v[92:95], v[160:163], v[200:203], v[92:95]
	v_mfma_f32_16x16x32_bf16 v[84:87], v[152:155], v[214:217], v[84:87]
	v_mfma_f32_16x16x32_bf16 v[76:79], v[160:163], v[214:217], v[76:79]
	v_mfma_f32_16x16x32_bf16 v[124:127], v[156:159], v[188:191], v[124:127]
	v_mfma_f32_16x16x32_bf16 v[120:123], v[164:167], v[188:191], v[120:123]
	v_mfma_f32_16x16x32_bf16 v[116:119], v[156:159], v[196:199], v[116:119]
	v_mfma_f32_16x16x32_bf16 v[108:111], v[164:167], v[196:199], v[108:111]
	v_mfma_f32_16x16x32_bf16 v[100:103], v[156:159], v[210:213], v[100:103]
	v_mfma_f32_16x16x32_bf16 v[92:95], v[164:167], v[210:213], v[92:95]
	v_mfma_f32_16x16x32_bf16 v[84:87], v[156:159], v[218:221], v[84:87]
	v_mfma_f32_16x16x32_bf16 v[76:79], v[164:167], v[218:221], v[76:79]
	v_mfma_f32_16x16x32_bf16 v[112:115], v[168:171], v[184:187], v[112:115]
	v_mfma_f32_16x16x32_bf16 v[104:107], v[176:179], v[184:187], v[104:107]
	v_mfma_f32_16x16x32_bf16 v[96:99], v[168:171], v[192:195], v[96:99]
	v_mfma_f32_16x16x32_bf16 v[88:91], v[176:179], v[192:195], v[88:91]
	v_mfma_f32_16x16x32_bf16 v[80:83], v[168:171], v[200:203], v[80:83]
	v_mfma_f32_16x16x32_bf16 v[72:75], v[176:179], v[200:203], v[72:75]
	v_mfma_f32_16x16x32_bf16 v[68:71], v[168:171], v[214:217], v[68:71]
	v_mfma_f32_16x16x32_bf16 v[64:67], v[176:179], v[214:217], v[64:67]
	v_mfma_f32_16x16x32_bf16 v[112:115], v[172:175], v[188:191], v[112:115]
	v_mfma_f32_16x16x32_bf16 v[104:107], v[180:183], v[188:191], v[104:107]
	v_mfma_f32_16x16x32_bf16 v[96:99], v[172:175], v[196:199], v[96:99]
	v_mfma_f32_16x16x32_bf16 v[88:91], v[180:183], v[196:199], v[88:91]
	v_mfma_f32_16x16x32_bf16 v[80:83], v[172:175], v[210:213], v[80:83]
	v_mfma_f32_16x16x32_bf16 v[72:75], v[180:183], v[210:213], v[72:75]
	v_mfma_f32_16x16x32_bf16 v[68:71], v[172:175], v[218:221], v[68:71]
	v_mfma_f32_16x16x32_bf16 v[64:67], v[180:183], v[218:221], v[64:67]
	s_barrier
	s_setprio 0
	s_add_u32 s100, s44, 0x80
	s_addc_u32 s101, s45, 0
	s_add_i32 m0, s69, s49
	ds_read_b128 v[184:187], v151 offset:49152
	ds_read_b128 v[188:191], v151 offset:50176
	ds_read_b128 v[192:195], v151 offset:51200
	ds_read_b128 v[196:199], v151 offset:52224
	global_load_lds_dwordx4 v130, s[100:101]
	s_add_i32 m0, m0, 0x2000
	s_add_u32 s0, s44, 0x100080
	s_addc_u32 s1, s45, 0
	s_add_i32 s44, s70, s49
	global_load_lds_dwordx4 v134, s[100:101]
	s_mov_b32 m0, s44
	ds_read_b128 v[218:221], v151 offset:56320
	global_load_lds_dwordx4 v130, s[0:1]
	s_add_i32 m0, s44, 0x2000
	ds_read_b128 v[214:217], v151 offset:55296
	global_load_lds_dwordx4 v134, s[0:1]
	s_add_u32 s100, s46, 0x80
	s_addc_u32 s101, s47, 0
	s_mov_b32 m0, s54
	ds_read_b128 v[210:213], v151 offset:54272
	global_load_lds_dwordx4 v128, s[100:101]
	s_mov_b32 m0, s55
	ds_read_b128 v[200:203], v151 offset:53248
	global_load_lds_dwordx4 v132, s[100:101]
	s_waitcnt vmcnt(8) lgkmcnt(0)
	s_setprio 3
	s_barrier
	v_mfma_f32_16x16x32_bf16 v[60:63], v[152:155], v[184:187], v[60:63]
	v_mfma_f32_16x16x32_bf16 v[56:59], v[160:163], v[184:187], v[56:59]
	v_mfma_f32_16x16x32_bf16 v[52:55], v[152:155], v[192:195], v[52:55]
	v_mfma_f32_16x16x32_bf16 v[44:47], v[160:163], v[192:195], v[44:47]
	v_mfma_f32_16x16x32_bf16 v[36:39], v[152:155], v[200:203], v[36:39]
	v_mfma_f32_16x16x32_bf16 v[28:31], v[160:163], v[200:203], v[28:31]
	v_mfma_f32_16x16x32_bf16 v[20:23], v[152:155], v[214:217], v[20:23]
	v_mfma_f32_16x16x32_bf16 v[12:15], v[160:163], v[214:217], v[12:15]
	v_mfma_f32_16x16x32_bf16 v[60:63], v[156:159], v[188:191], v[60:63]
	v_mfma_f32_16x16x32_bf16 v[56:59], v[164:167], v[188:191], v[56:59]
	v_mfma_f32_16x16x32_bf16 v[52:55], v[156:159], v[196:199], v[52:55]
	v_mfma_f32_16x16x32_bf16 v[44:47], v[164:167], v[196:199], v[44:47]
	v_mfma_f32_16x16x32_bf16 v[36:39], v[156:159], v[210:213], v[36:39]
	v_mfma_f32_16x16x32_bf16 v[28:31], v[164:167], v[210:213], v[28:31]
	v_mfma_f32_16x16x32_bf16 v[20:23], v[156:159], v[218:221], v[20:23]
	v_mfma_f32_16x16x32_bf16 v[12:15], v[164:167], v[218:221], v[12:15]
	s_add_u32 s42, s42, 0x100
	s_addc_u32 s43, s43, 0
	s_add_i32 s68, s68, 2
	s_add_u32 s66, s66, 0x100
	s_addc_u32 s67, s67, 0
	v_mfma_f32_16x16x32_bf16 v[48:51], v[168:171], v[184:187], v[48:51]
	v_mfma_f32_16x16x32_bf16 v[40:43], v[176:179], v[184:187], v[40:43]
	v_mfma_f32_16x16x32_bf16 v[32:35], v[168:171], v[192:195], v[32:35]
	v_mfma_f32_16x16x32_bf16 v[24:27], v[176:179], v[192:195], v[24:27]
	v_mfma_f32_16x16x32_bf16 v[16:19], v[168:171], v[200:203], v[16:19]
	v_mfma_f32_16x16x32_bf16 v[8:11], v[176:179], v[200:203], v[8:11]
	v_mfma_f32_16x16x32_bf16 v[4:7], v[168:171], v[214:217], v[4:7]
	v_mfma_f32_16x16x32_bf16 v[0:3], v[176:179], v[214:217], v[0:3]
	v_mfma_f32_16x16x32_bf16 v[48:51], v[172:175], v[188:191], v[48:51]
	v_mfma_f32_16x16x32_bf16 v[40:43], v[180:183], v[188:191], v[40:43]
	v_mfma_f32_16x16x32_bf16 v[32:35], v[172:175], v[196:199], v[32:35]
	v_mfma_f32_16x16x32_bf16 v[24:27], v[180:183], v[196:199], v[24:27]
	v_mfma_f32_16x16x32_bf16 v[16:19], v[172:175], v[210:213], v[16:19]
	v_mfma_f32_16x16x32_bf16 v[8:11], v[180:183], v[210:213], v[8:11]
	v_mfma_f32_16x16x32_bf16 v[4:7], v[172:175], v[218:221], v[4:7]
	v_mfma_f32_16x16x32_bf16 v[0:3], v[180:183], v[218:221], v[0:3]
	s_barrier
	s_setprio 0
	s_cmp_gt_u32 s68, 61
	s_cbranch_scc0 .LBB0_1637
	s_and_b64 vcc, exec, s[16:17]
	s_cbranch_vccz .LBB0_1640
	s_barrier

.LBB0_1813:
	ds_read_b128 v[148:151], v156
	ds_read_b128 v[160:163], v156 offset:1024
	ds_read_b128 v[164:167], v156 offset:2048
	ds_read_b128 v[168:171], v156 offset:3072
	ds_read_b128 v[172:175], v157
	ds_read_b128 v[176:179], v157 offset:1024
	ds_read_b128 v[180:183], v157 offset:2048
	ds_read_b128 v[184:187], v157 offset:3072
	s_add_u32 s0, s36, 0xfff00080
	s_addc_u32 s1, s37, -1
	s_cmp_eq_u32 s64, 60
	s_cselect_b32 s41, s59, s1
	s_cselect_b32 s40, s60, s0
	s_cselect_b32 s39, s17, s63
	s_cselect_b32 s38, s61, s62
	s_add_i32 m0, s31, 0xc000
	ds_read_b128 v[188:191], v158
	ds_read_b128 v[192:195], v158 offset:1024
	ds_read_b128 v[196:199], v158 offset:2048
	ds_read_b128 v[200:203], v158 offset:3072
	ds_read_b128 v[210:213], v158 offset:4096
	ds_read_b128 v[214:217], v158 offset:5120
	ds_read_b128 v[218:221], v158 offset:6144
	global_load_lds_dwordx4 v140, s[36:37]
	s_add_i32 m0, s31, 0xe000
	ds_read_b128 v[222:225], v158 offset:7168
	global_load_lds_dwordx4 v142, s[36:37]
	s_waitcnt vmcnt(8) lgkmcnt(0)
	s_setprio 3
	s_barrier
	v_mfma_f32_16x16x32_bf16 v[124:127], v[148:151], v[188:191], v[124:127]
	v_mfma_f32_16x16x32_bf16 v[120:123], v[164:167], v[188:191], v[120:123]
	v_mfma_f32_16x16x32_bf16 v[108:111], v[148:151], v[196:199], v[108:111]
	v_mfma_f32_16x16x32_bf16 v[104:107], v[164:167], v[196:199], v[104:107]
	v_mfma_f32_16x16x32_bf16 v[92:95], v[148:151], v[210:213], v[92:95]
	v_mfma_f32_16x16x32_bf16 v[88:91], v[164:167], v[210:213], v[88:91]
	v_mfma_f32_16x16x32_bf16 v[76:79], v[148:151], v[218:221], v[76:79]
	v_mfma_f32_16x16x32_bf16 v[72:75], v[164:167], v[218:221], v[72:75]
	v_mfma_f32_16x16x32_bf16 v[124:127], v[160:163], v[192:195], v[124:127]
	v_mfma_f32_16x16x32_bf16 v[120:123], v[168:171], v[192:195], v[120:123]
	v_mfma_f32_16x16x32_bf16 v[108:111], v[160:163], v[200:203], v[108:111]
	v_mfma_f32_16x16x32_bf16 v[104:107], v[168:171], v[200:203], v[104:107]
	v_mfma_f32_16x16x32_bf16 v[92:95], v[160:163], v[214:217], v[92:95]
	v_mfma_f32_16x16x32_bf16 v[88:91], v[168:171], v[214:217], v[88:91]
	v_mfma_f32_16x16x32_bf16 v[76:79], v[160:163], v[222:225], v[76:79]
	v_mfma_f32_16x16x32_bf16 v[72:75], v[168:171], v[222:225], v[72:75]
	v_mfma_f32_16x16x32_bf16 v[116:119], v[172:175], v[188:191], v[116:119]
	v_mfma_f32_16x16x32_bf16 v[112:115], v[180:183], v[188:191], v[112:115]
	v_mfma_f32_16x16x32_bf16 v[100:103], v[172:175], v[196:199], v[100:103]
	v_mfma_f32_16x16x32_bf16 v[96:99], v[180:183], v[196:199], v[96:99]
	v_mfma_f32_16x16x32_bf16 v[84:87], v[172:175], v[210:213], v[84:87]
	v_mfma_f32_16x16x32_bf16 v[80:83], v[180:183], v[210:213], v[80:83]
	v_mfma_f32_16x16x32_bf16 v[68:71], v[172:175], v[218:221], v[68:71]
	v_mfma_f32_16x16x32_bf16 v[64:67], v[180:183], v[218:221], v[64:67]
	v_mfma_f32_16x16x32_bf16 v[116:119], v[176:179], v[192:195], v[116:119]
	v_mfma_f32_16x16x32_bf16 v[112:115], v[184:187], v[192:195], v[112:115]
	v_mfma_f32_16x16x32_bf16 v[100:103], v[176:179], v[200:203], v[100:103]
	v_mfma_f32_16x16x32_bf16 v[96:99], v[184:187], v[200:203], v[96:99]
	v_mfma_f32_16x16x32_bf16 v[84:87], v[176:179], v[214:217], v[84:87]
	v_mfma_f32_16x16x32_bf16 v[80:83], v[184:187], v[214:217], v[80:83]
	v_mfma_f32_16x16x32_bf16 v[68:71], v[176:179], v[222:225], v[68:71]
	v_mfma_f32_16x16x32_bf16 v[64:67], v[184:187], v[222:225], v[64:67]
	s_barrier
	s_setprio 0
	s_add_i32 m0, s52, s43
	ds_read_b128 v[188:191], v158 offset:16384
	ds_read_b128 v[192:195], v158 offset:17408
	ds_read_b128 v[196:199], v158 offset:18432
	ds_read_b128 v[200:203], v158 offset:19456
	ds_read_b128 v[210:213], v158 offset:20480
	global_load_lds_dwordx4 v132, s[38:39]
	s_add_i32 m0, m0, 0x2000
	s_add_u32 s0, s38, 0x100000
	s_addc_u32 s1, s39, 0
	s_add_i32 s65, s53, s43
	global_load_lds_dwordx4 v136, s[38:39]
	s_mov_b32 m0, s65
	s_nop 0
	global_load_lds_dwordx4 v132, s[0:1]
	s_add_i32 m0, s65, 0x2000
	ds_read_b128 v[222:225], v158 offset:23552
	global_load_lds_dwordx4 v136, s[0:1]
	s_mov_b32 m0, s31
	ds_read_b128 v[218:221], v158 offset:22528
	global_load_lds_dwordx4 v130, s[40:41]
	s_mov_b32 m0, s35
	ds_read_b128 v[214:217], v158 offset:21504
	global_load_lds_dwordx4 v134, s[40:41]
	s_waitcnt vmcnt(8) lgkmcnt(0)
	s_setprio 3
	s_barrier
	v_mfma_f32_16x16x32_bf16 v[60:63], v[148:151], v[188:191], v[60:63]
	v_mfma_f32_16x16x32_bf16 v[56:59], v[164:167], v[188:191], v[56:59]
	v_mfma_f32_16x16x32_bf16 v[44:47], v[148:151], v[196:199], v[44:47]
	v_mfma_f32_16x16x32_bf16 v[40:43], v[164:167], v[196:199], v[40:43]
	v_mfma_f32_16x16x32_bf16 v[28:31], v[148:151], v[210:213], v[28:31]
	v_mfma_f32_16x16x32_bf16 v[24:27], v[164:167], v[210:213], v[24:27]
	v_mfma_f32_16x16x32_bf16 v[12:15], v[148:151], v[218:221], v[12:15]
	v_mfma_f32_16x16x32_bf16 v[8:11], v[164:167], v[218:221], v[8:11]
	v_mfma_f32_16x16x32_bf16 v[60:63], v[160:163], v[192:195], v[60:63]
	v_mfma_f32_16x16x32_bf16 v[56:59], v[168:171], v[192:195], v[56:59]
	v_mfma_f32_16x16x32_bf16 v[44:47], v[160:163], v[200:203], v[44:47]
	v_mfma_f32_16x16x32_bf16 v[40:43], v[168:171], v[200:203], v[40:43]
	v_mfma_f32_16x16x32_bf16 v[28:31], v[160:163], v[214:217], v[28:31]
	v_mfma_f32_16x16x32_bf16 v[24:27], v[168:171], v[214:217], v[24:27]
	v_mfma_f32_16x16x32_bf16 v[12:15], v[160:163], v[222:225], v[12:15]
	v_mfma_f32_16x16x32_bf16 v[8:11], v[168:171], v[222:225], v[8:11]
	v_mfma_f32_16x16x32_bf16 v[52:55], v[172:175], v[188:191], v[52:55]
	v_mfma_f32_16x16x32_bf16 v[48:51], v[180:183], v[188:191], v[48:51]
	v_mfma_f32_16x16x32_bf16 v[36:39], v[172:175], v[196:199], v[36:39]
	v_mfma_f32_16x16x32_bf16 v[32:35], v[180:183], v[196:199], v[32:35]
	v_mfma_f32_16x16x32_bf16 v[20:23], v[172:175], v[210:213], v[20:23]
	v_mfma_f32_16x16x32_bf16 v[16:19], v[180:183], v[210:213], v[16:19]
	v_mfma_f32_16x16x32_bf16 v[4:7], v[172:175], v[218:221], v[4:7]
	v_mfma_f32_16x16x32_bf16 v[0:3], v[180:183], v[218:221], v[0:3]
	v_mfma_f32_16x16x32_bf16 v[52:55], v[176:179], v[192:195], v[52:55]
	v_mfma_f32_16x16x32_bf16 v[48:51], v[184:187], v[192:195], v[48:51]
	v_mfma_f32_16x16x32_bf16 v[36:39], v[176:179], v[200:203], v[36:39]
	v_mfma_f32_16x16x32_bf16 v[32:35], v[184:187], v[200:203], v[32:35]
	v_mfma_f32_16x16x32_bf16 v[20:23], v[176:179], v[214:217], v[20:23]
	v_mfma_f32_16x16x32_bf16 v[16:19], v[184:187], v[214:217], v[16:19]
	v_mfma_f32_16x16x32_bf16 v[4:7], v[176:179], v[222:225], v[4:7]
	v_mfma_f32_16x16x32_bf16 v[0:3], v[184:187], v[222:225], v[0:3]
	s_barrier
	s_setprio 0
	s_add_i32 s65, 0, 0x18000
	s_add_i32 s66, 0, 0x1c000
	ds_read_b128 v[148:151], v234
	ds_read_b128 v[160:163], v234 offset:1024
	ds_read_b128 v[164:167], v234 offset:2048
	ds_read_b128 v[168:171], v234 offset:3072
	ds_read_b128 v[172:175], v235
	ds_read_b128 v[176:179], v235 offset:1024
	ds_read_b128 v[180:183], v235 offset:2048
	ds_read_b128 v[184:187], v235 offset:3072
	s_add_u32 s0, s40, 0x100000
	s_addc_u32 s1, s41, 0
	s_mov_b32 m0, s44
	ds_read_b128 v[188:191], v158 offset:32768
	ds_read_b128 v[192:195], v158 offset:33792
	ds_read_b128 v[196:199], v158 offset:34816
	ds_read_b128 v[200:203], v158 offset:35840
	ds_read_b128 v[210:213], v158 offset:36864
	ds_read_b128 v[214:217], v158 offset:37888
	ds_read_b128 v[218:221], v158 offset:38912
	global_load_lds_dwordx4 v130, s[0:1]
	s_mov_b32 m0, s45
	ds_read_b128 v[222:225], v158 offset:39936
	global_load_lds_dwordx4 v134, s[0:1]
	s_waitcnt vmcnt(8) lgkmcnt(0)
	s_setprio 3
	s_barrier
	v_mfma_f32_16x16x32_bf16 v[124:127], v[148:151], v[188:191], v[124:127]
	v_mfma_f32_16x16x32_bf16 v[120:123], v[164:167], v[188:191], v[120:123]
	v_mfma_f32_16x16x32_bf16 v[108:111], v[148:151], v[196:199], v[108:111]
	v_mfma_f32_16x16x32_bf16 v[104:107], v[164:167], v[196:199], v[104:107]
	v_mfma_f32_16x16x32_bf16 v[92:95], v[148:151], v[210:213], v[92:95]
	v_mfma_f32_16x16x32_bf16 v[88:91], v[164:167], v[210:213], v[88:91]
	v_mfma_f32_16x16x32_bf16 v[76:79], v[148:151], v[218:221], v[76:79]
	v_mfma_f32_16x16x32_bf16 v[72:75], v[164:167], v[218:221], v[72:75]
	v_mfma_f32_16x16x32_bf16 v[124:127], v[160:163], v[192:195], v[124:127]
	v_mfma_f32_16x16x32_bf16 v[120:123], v[168:171], v[192:195], v[120:123]
	v_mfma_f32_16x16x32_bf16 v[108:111], v[160:163], v[200:203], v[108:111]
	v_mfma_f32_16x16x32_bf16 v[104:107], v[168:171], v[200:203], v[104:107]
	v_mfma_f32_16x16x32_bf16 v[92:95], v[160:163], v[214:217], v[92:95]
	v_mfma_f32_16x16x32_bf16 v[88:91], v[168:171], v[214:217], v[88:91]
	v_mfma_f32_16x16x32_bf16 v[76:79], v[160:163], v[222:225], v[76:79]
	v_mfma_f32_16x16x32_bf16 v[72:75], v[168:171], v[222:225], v[72:75]
	v_mfma_f32_16x16x32_bf16 v[116:119], v[172:175], v[188:191], v[116:119]
	v_mfma_f32_16x16x32_bf16 v[112:115], v[180:183], v[188:191], v[112:115]
	v_mfma_f32_16x16x32_bf16 v[100:103], v[172:175], v[196:199], v[100:103]
	v_mfma_f32_16x16x32_bf16 v[96:99], v[180:183], v[196:199], v[96:99]
	v_mfma_f32_16x16x32_bf16 v[84:87], v[172:175], v[210:213], v[84:87]
	v_mfma_f32_16x16x32_bf16 v[80:83], v[180:183], v[210:213], v[80:83]
	v_mfma_f32_16x16x32_bf16 v[68:71], v[172:175], v[218:221], v[68:71]
	v_mfma_f32_16x16x32_bf16 v[64:67], v[180:183], v[218:221], v[64:67]
	v_mfma_f32_16x16x32_bf16 v[116:119], v[176:179], v[192:195], v[116:119]
	v_mfma_f32_16x16x32_bf16 v[112:115], v[184:187], v[192:195], v[112:115]
	v_mfma_f32_16x16x32_bf16 v[100:103], v[176:179], v[200:203], v[100:103]
	v_mfma_f32_16x16x32_bf16 v[96:99], v[184:187], v[200:203], v[96:99]
	v_mfma_f32_16x16x32_bf16 v[84:87], v[176:179], v[214:217], v[84:87]
	v_mfma_f32_16x16x32_bf16 v[80:83], v[184:187], v[214:217], v[80:83]
	v_mfma_f32_16x16x32_bf16 v[68:71], v[176:179], v[222:225], v[68:71]
	v_mfma_f32_16x16x32_bf16 v[64:67], v[184:187], v[222:225], v[64:67]
	s_barrier
	s_setprio 0
	s_add_u32 s100, s38, 0x80
	s_addc_u32 s101, s39, 0
	s_add_i32 m0, s65, s43
	ds_read_b128 v[188:191], v158 offset:49152
	ds_read_b128 v[192:195], v158 offset:50176
	ds_read_b128 v[196:199], v158 offset:51200
	ds_read_b128 v[200:203], v158 offset:52224
	global_load_lds_dwordx4 v132, s[100:101]
	s_add_i32 m0, m0, 0x2000
	s_add_u32 s0, s38, 0x100080
	s_addc_u32 s1, s39, 0
	s_add_i32 s38, s66, s43
	global_load_lds_dwordx4 v136, s[100:101]
	s_mov_b32 m0, s38
	ds_read_b128 v[222:225], v158 offset:56320
	global_load_lds_dwordx4 v132, s[0:1]
	s_add_i32 m0, s38, 0x2000
	ds_read_b128 v[218:221], v158 offset:55296
	global_load_lds_dwordx4 v136, s[0:1]
	s_add_u32 s100, s40, 0x80
	s_addc_u32 s101, s41, 0
	s_mov_b32 m0, s49
	ds_read_b128 v[214:217], v158 offset:54272
	global_load_lds_dwordx4 v130, s[100:101]
	s_mov_b32 m0, s50
	ds_read_b128 v[210:213], v158 offset:53248
	global_load_lds_dwordx4 v134, s[100:101]
	s_waitcnt vmcnt(8) lgkmcnt(0)
	s_setprio 3
	s_barrier
	v_mfma_f32_16x16x32_bf16 v[60:63], v[148:151], v[188:191], v[60:63]
	v_mfma_f32_16x16x32_bf16 v[56:59], v[164:167], v[188:191], v[56:59]
	v_mfma_f32_16x16x32_bf16 v[44:47], v[148:151], v[196:199], v[44:47]
	v_mfma_f32_16x16x32_bf16 v[40:43], v[164:167], v[196:199], v[40:43]
	v_mfma_f32_16x16x32_bf16 v[28:31], v[148:151], v[210:213], v[28:31]
	v_mfma_f32_16x16x32_bf16 v[24:27], v[164:167], v[210:213], v[24:27]
	v_mfma_f32_16x16x32_bf16 v[12:15], v[148:151], v[218:221], v[12:15]
	v_mfma_f32_16x16x32_bf16 v[8:11], v[164:167], v[218:221], v[8:11]
	v_mfma_f32_16x16x32_bf16 v[60:63], v[160:163], v[192:195], v[60:63]
	v_mfma_f32_16x16x32_bf16 v[56:59], v[168:171], v[192:195], v[56:59]
	v_mfma_f32_16x16x32_bf16 v[44:47], v[160:163], v[200:203], v[44:47]
	v_mfma_f32_16x16x32_bf16 v[40:43], v[168:171], v[200:203], v[40:43]
	v_mfma_f32_16x16x32_bf16 v[28:31], v[160:163], v[214:217], v[28:31]
	v_mfma_f32_16x16x32_bf16 v[24:27], v[168:171], v[214:217], v[24:27]
	v_mfma_f32_16x16x32_bf16 v[12:15], v[160:163], v[222:225], v[12:15]
	v_mfma_f32_16x16x32_bf16 v[8:11], v[168:171], v[222:225], v[8:11]
	s_add_u32 s36, s36, 0x100
	s_addc_u32 s37, s37, 0
	s_add_i32 s64, s64, 2
	s_add_u32 s62, s62, 0x100
	s_addc_u32 s63, s63, 0
	v_mfma_f32_16x16x32_bf16 v[52:55], v[172:175], v[188:191], v[52:55]
	v_mfma_f32_16x16x32_bf16 v[48:51], v[180:183], v[188:191], v[48:51]
	v_mfma_f32_16x16x32_bf16 v[36:39], v[172:175], v[196:199], v[36:39]
	v_mfma_f32_16x16x32_bf16 v[32:35], v[180:183], v[196:199], v[32:35]
	v_mfma_f32_16x16x32_bf16 v[20:23], v[172:175], v[210:213], v[20:23]
	v_mfma_f32_16x16x32_bf16 v[16:19], v[180:183], v[210:213], v[16:19]
	v_mfma_f32_16x16x32_bf16 v[4:7], v[172:175], v[218:221], v[4:7]
	v_mfma_f32_16x16x32_bf16 v[0:3], v[180:183], v[218:221], v[0:3]
	v_mfma_f32_16x16x32_bf16 v[52:55], v[176:179], v[192:195], v[52:55]
	v_mfma_f32_16x16x32_bf16 v[48:51], v[184:187], v[192:195], v[48:51]
	v_mfma_f32_16x16x32_bf16 v[36:39], v[176:179], v[200:203], v[36:39]
	v_mfma_f32_16x16x32_bf16 v[32:35], v[184:187], v[200:203], v[32:35]
	v_mfma_f32_16x16x32_bf16 v[20:23], v[176:179], v[214:217], v[20:23]
	v_mfma_f32_16x16x32_bf16 v[16:19], v[184:187], v[214:217], v[16:19]
	v_mfma_f32_16x16x32_bf16 v[4:7], v[176:179], v[222:225], v[4:7]
	v_mfma_f32_16x16x32_bf16 v[0:3], v[184:187], v[222:225], v[0:3]
	s_barrier
	s_setprio 0
	s_cmp_gt_u32 s64, 61
	s_cbranch_scc0 .LBB0_1813
	s_and_b64 vcc, exec, s[14:15]
	s_cbranch_vccz .LBB0_1816
	s_barrier
